# attention key loop back-edge rotation: fragment-read address arithmetic computed in front of the loop barrier
# baseline (speedup 1.0000x reference)
; DI void attn_item(const Params& p, int l, bool isS, int b, int h, int cp, char* smem) {
;     ...
;   if (wactive) {
;     f32x4 st[2][4];
;     float alpha[2], psum[2]; bool moved[2];
;     qk_tile(0, st);
;     softmax_tile(st, pf, alpha, psum, moved);
;     apply_scale(alpha, psum, moved);
;   }
;   asm volatile("s_waitcnt lgkmcnt(0)" ::: "memory");
;   __builtin_amdgcn_s_barrier();
;   for (int j = 0; j < nkt; ++j) {
;     if (j + 2 < nkt) issue_k(j + 2);
;     if (j + 1 < nkt) issue_v(j + 1);
;     const bool doPV = wactive && j < mykt;
;     const bool doQK = wactive && j + 1 < mykt;
;     f32x4 st[2][4];
;     bf16x8 pfn[2][2];
;     float alpha[2] = {1.f, 1.f}, psum[2] = {0.f, 0.f}; bool moved[2] = {false, false};
;     auto pv_tile = [&]() {
;       const char* Vb = Vs + (j & 1) * 16384;
; #pragma unroll
;       for (int nh = 0; nh < 2; ++nh) {
;         bf16x8 vf[4][2];
; #pragma unroll
;         for (int n = 0; n < 4; ++n) {
;           const int vd = (nh * 4 + n) * 16 + fr;
; #pragma unroll
;           for (int s = 0; s < 2; ++s) vf[n][s] = *(const bf16x8*)(Vb + vd * 128 + (((s * 4 + fq) ^ ((vd >> 1) & 7)) << 4));
.LBB0_1366:
	s_or_b64 exec, exec, s[30:31]
	s_waitcnt lgkmcnt(0)
	s_cmp_lt_i32 s9, 1
	s_barrier
	s_cbranch_scc1 .LBB0_1387
	s_or_b32 s11, s11, 1
	v_mov_b32_e32 v2, s20
	v_mov_b32_e32 v20, s11
	v_cmp_gt_i32_e32 vcc, 4, v57
	v_bfe_u32 v21, v54, 1, 3
	v_mov_b32_e32 v53, v173
	v_cndmask_b32_e32 v2, v2, v20, vcc
	v_lshrrev_b32_e32 v20, 1, v54
	v_bitop3_b32 v20, v56, v20, 7 bitop3:0x78
	v_lshlrev_b32_e32 v137, 4, v20
	v_bitop3_b32 v20, v56, v21, 4 bitop3:0x36
	v_lshl_add_u64 v[142:143], s[28:29], 0, v[52:53]
	v_lshlrev_b32_e32 v145, 4, v20
	v_lshlrev_b32_e32 v146, 4, v59
	v_lshlrev_b32_e32 v147, 4, v60
	v_lshlrev_b32_e32 v148, 4, v61
	v_lshlrev_b32_e32 v149, 4, v62
	v_lshl_add_u32 v150, v55, 7, 16
	v_lshl_add_u32 v151, v58, 8, 16
	v_mov_b64_e32 v[58:59], v[26:27]
	v_mov_b64_e32 v[66:67], v[26:27]
	v_mov_b64_e32 v[70:71], v[26:27]
	v_mov_b64_e32 v[20:21], v[76:77]
	v_mov_b64_e32 v[36:37], v[76:77]
	v_mov_b64_e32 v[40:41], v[76:77]
	v_mov_b64_e32 v[48:49], v[76:77]
	v_mov_b64_e32 v[52:53], v[76:77]
	v_mov_b64_e32 v[60:61], v[76:77]
	v_mov_b64_e32 v[72:73], v[76:77]
	v_mov_b64_e32 v[46:47], v[26:27]
	v_mov_b64_e32 v[34:35], v[26:27]
	v_mov_b64_e32 v[30:31], v[26:27]
	v_mov_b64_e32 v[82:83], v[26:27]
	v_cndmask_b32_e64 v2, v2, 33, s[26:27]
	s_mov_b32 s11, 0
	s_xor_b64 s[26:27], s[12:13], -1
	s_mov_b32 s34, 0
	v_mov_b64_e32 v[56:57], v[24:25]
	v_mov_b64_e32 v[64:65], v[24:25]
	v_mov_b64_e32 v[68:69], v[24:25]
	v_mov_b64_e32 v[22:23], v[78:79]
	v_mov_b64_e32 v[38:39], v[78:79]
	v_mov_b64_e32 v[42:43], v[78:79]
	v_mov_b64_e32 v[50:51], v[78:79]
	v_mov_b64_e32 v[54:55], v[78:79]
	v_mov_b64_e32 v[62:63], v[78:79]
	v_mov_b64_e32 v[74:75], v[78:79]
	v_mov_b64_e32 v[44:45], v[24:25]
	v_mov_b64_e32 v[32:33], v[24:25]
	v_mov_b64_e32 v[28:29], v[24:25]
	v_mov_b64_e32 v[80:81], v[24:25]
	s_mov_b32 s30, 0
	s_add_i32 s20, s34, 0x4000
	s_and_b32 s20, s20, 0x4000
	v_add_u32_e32 v248, s20, v151
	v_add_u32_e32 v170, v248, v146
	v_add_u32_e32 v171, v248, v147
	v_add_u32_e32 v242, v248, v148
	v_add_u32_e32 v243, v248, v149
	s_and_b32 s24, s34, 0x4000
	v_add_u32_e32 v249, s24, v150
	v_add_u32_e32 v244, v249, v137
	v_add_u32_e32 v245, v249, v145
	s_branch .LBB0_1370

; #define MFMA16(a, b, c) __builtin_amdgcn_mfma_f32_16x16x32_bf16((a), (b), (c), 0, 0, 0)
; DI int kswz(int key) { return (((key >> 3) & 3) << 2) | (key & 3); }
; DI void attn_item(const Params& p, int l, bool isS, int b, int h, int cp, char* smem) {
;     ...
;   auto issue_k = [&](int kt) {
; #pragma unroll
;     for (int i = 0; i < 2; ++i)
;       __builtin_amdgcn_global_load_lds((const unsigned*)(Kg + (size_t)(kt * 64 + kkey + i * 32) * 512 + kgch * 8), (unsigned*)(Ks + (kt & 1) * 16384 + soff + i * 8192), 16, 0, 0);
;   };
;     ...
;   auto qk_tile = [&](int kt, f32x4 (&st)[2][4]) {
;     const char* Kb = Ks + (kt & 1) * 16384;
;     bf16x8 kf[2][4][2];
; #pragma unroll
;     for (int mp = 0; mp < 2; ++mp)
; #pragma unroll
;       for (int mt = 0; mt < 4; ++mt) {
;         const int key = 32 * (mt >> 1) + 8 * (fr >> 2) + 4 * (mt & 1) + (fr & 3);
; #pragma unroll
;         for (int ks = 0; ks < 2; ++ks) kf[mp][mt][ks] = *(const bf16x8*)(Kb + key * 256 + (((mp * 8 + ks * 4 + fq) ^ kswz(key)) << 4));
;       }
; #pragma unroll
;     for (int mp = 0; mp < 2; ++mp)
; #pragma unroll
;       for (int mt = 0; mt < 4; ++mt) {
;         f32x4 a = MFMA16(kf[mp][mt][0], qf[mp][0], (f32x4{0.f, 0.f, 0.f, 0.f}));
;         st[mp][mt] = MFMA16(kf[mp][mt][1], qf[mp][1], a);
.LBB0_1369:
.LBB0_1370:
	ds_read_b128 v[154:157], v170
	ds_read_b128 v[158:161], v171
	ds_read_b128 v[162:165], v170 offset:1024
	ds_read_b128 v[166:169], v171 offset:1024
	ds_read_b128 v[176:179], v170 offset:8192
	ds_read_b128 v[180:183], v171 offset:8192
	ds_read_b128 v[198:201], v170 offset:9216
	ds_read_b128 v[202:205], v171 offset:9216
	ds_read_b128 v[206:209], v242
	ds_read_b128 v[214:217], v243
	ds_read_b128 v[218:221], v242 offset:1024
	ds_read_b128 v[222:225], v243 offset:1024
	ds_read_b128 v[226:229], v242 offset:8192
	ds_read_b128 v[230:233], v243 offset:8192
	ds_read_b128 v[234:237], v242 offset:9216
	s_waitcnt lgkmcnt(13)
	v_mfma_f32_16x16x32_bf16 v[124:127], v[154:157], v[8:11], 0
	v_mfma_f32_16x16x32_bf16 v[124:127], v[158:161], v[4:7], v[124:127]
	ds_read_b128 v[238:241], v243 offset:9216
	s_waitcnt lgkmcnt(12)
	v_mfma_f32_16x16x32_bf16 v[120:123], v[162:165], v[8:11], 0
	v_mfma_f32_16x16x32_bf16 v[120:123], v[166:169], v[4:7], v[120:123]
	s_waitcnt lgkmcnt(10)
	v_mfma_f32_16x16x32_bf16 v[112:115], v[176:179], v[8:11], 0
	v_mfma_f32_16x16x32_bf16 v[112:115], v[180:183], v[4:7], v[112:115]
	s_waitcnt lgkmcnt(8)
	v_mfma_f32_16x16x32_bf16 v[116:119], v[198:201], v[8:11], 0
	v_mfma_f32_16x16x32_bf16 v[116:119], v[202:205], v[4:7], v[116:119]
	s_add_i32 s20, s30, 2
	s_cmp_ge_i32 s20, s9
	s_cbranch_scc1 .Lat_nokdma
	v_add_u32_e32 v102, s11, v136
	s_and_b32 s20, s34, 0x4000
	v_add_u32_e32 v100, 0x80, v102
	v_ashrrev_i32_e32 v101, 31, v100
	v_add_u32_e32 v103, s20, v133
	v_lshlrev_b64 v[100:101], 10, v[100:101]
	v_readfirstlane_b32 s20, v103
	v_lshl_add_u64 v[100:101], v[142:143], 0, v[100:101]
	s_mov_b32 m0, s20
	s_nop 0
	global_load_lds_dwordx4 v[100:101], off
	v_add_u32_e32 v100, 0xa0, v102
	v_ashrrev_i32_e32 v101, 31, v100
	v_add_u32_e32 v102, 0x2000, v103
	v_lshlrev_b64 v[100:101], 10, v[100:101]
	v_readfirstlane_b32 s20, v102
	v_lshl_add_u64 v[100:101], v[142:143], 0, v[100:101]
	s_mov_b32 m0, s20
	s_nop 0
	global_load_lds_dwordx4 v[100:101], off

; DI void attn_item(const Params& p, int l, bool isS, int b, int h, int cp, char* smem) {
;     ...
;   auto qk_tile = [&](int kt, f32x4 (&st)[2][4]) {
;     const char* Kb = Ks + (kt & 1) * 16384;
;     ...
;     asm volatile("s_waitcnt vmcnt(0) lgkmcnt(0)" ::: "memory");
;     __builtin_amdgcn_s_barrier();
.LBB0_1386:
	s_or_b64 exec, exec, s[28:29]
	s_waitcnt vmcnt(0) lgkmcnt(0)
	s_addk_i32 s34, 0x4000
	s_add_i32 s20, s34, 0x4000
	s_and_b32 s20, s20, 0x4000
	v_add_u32_e32 v248, s20, v151
	v_add_u32_e32 v170, v248, v146
	v_add_u32_e32 v171, v248, v147
	v_add_u32_e32 v242, v248, v148
	v_add_u32_e32 v243, v248, v149
	s_and_b32 s24, s34, 0x4000
	v_add_u32_e32 v249, s24, v150
	v_add_u32_e32 v244, v249, v137
	v_add_u32_e32 v245, v249, v145
	s_add_i32 s11, s11, 64
	s_cmp_eq_u32 s9, s35
	s_barrier
	s_cbranch_scc0 .LBB0_1368
	s_branch .LBB0_1388
